# GEMM K-loops: prefetch loads use SGPR base + 32-bit lane offsets (no 64-bit VALU address chains in the loop)
# speedup vs baseline: 1.0766x; 1.0174x over previous
; template <bool SWAP, class Epi>
; DI void gemm_tile(const u16* __restrict__ A, int lda, const u16* __restrict__ Bt, int ldb, int K, int m0, int n0, char* smem, Epi&& epi) {
;   u16* As = (u16*)(smem + 16);
;   u16* Bs = As + 2 * 128 * 72;
;   const int tid = threadIdx.x, lane = tid & 63, w = tid >> 6, wm = w >> 1, wn = w & 1;
;   const int r = lane & 31, hi = lane >> 5;
;   f32x16 acc[2][2];
; #pragma unroll
;   for (int a = 0; a < 2; ++a)
; #pragma unroll
;     for (int b = 0; b < 2; ++b)
; #pragma unroll
;       for (int i = 0; i < 16; ++i) acc[a][b][i] = 0.f;
;   const int srow = tid >> 3, skc = tid & 7;
;   const u16* ag = A + (size_t)(m0 + srow) * lda + skc * 8;
;   const u16* bg = Bt + (size_t)(n0 + srow) * ldb + skc * 8;
;   u16* asw = As + srow * 72 + skc * 8;
;   u16* bsw = Bs + srow * 72 + skc * 8;
;   u32x4 ra0[4], rb0[4], ra1[4], rb1[4];
; #pragma unroll
;   for (int i = 0; i < 4; ++i) { ra0[i] = *(const u32x4*)(ag + (size_t)i * 32 * lda); rb0[i] = *(const u32x4*)(bg + (size_t)i * 32 * ldb); }
; #pragma unroll
;   for (int i = 0; i < 4; ++i) { ra1[i] = *(const u32x4*)(ag + (size_t)i * 32 * lda + 64); rb1[i] = *(const u32x4*)(bg + (size_t)i * 32 * ldb + 64); }
;   __syncthreads();
; #pragma unroll
;   for (int i = 0; i < 4; ++i) { *(u32x4*)(asw + 32 * i * 72) = ra0[i]; *(u32x4*)(bsw + 32 * i * 72) = rb0[i]; }
;   __syncthreads();
;   const int KT = K >> 6;
;   const u16* Asb = As + (wm * 64 + r) * 72 + hi * 8;
;   const u16* Bsb = Bs + (wn * 64 + r) * 72 + hi * 8;
.LBB0_385:
	s_ashr_i32 s10, s21, 31
	s_lshr_b32 s10, s10, 26
	s_add_i32 s10, s21, s10
	s_and_b32 s11, s10, 0x1ffffc0
	s_sub_i32 s11, s21, s11
	s_lshl_b32 s22, s11, 7
	s_lshl_b32 s10, s10, 1
	s_waitcnt lgkmcnt(0)
	v_or_b32_e32 v2, s22, v1
	s_and_b32 s23, s10, 0xffffff80
	v_ashrrev_i32_e32 v3, 31, v2
	v_lshlrev_b64 v[22:23], 12, v[2:3]
	v_or_b32_e32 v2, s23, v1
	v_lshl_add_u64 v[4:5], v[132:133], 0, v[22:23]
	v_ashrrev_i32_e32 v3, 31, v2
	v_lshlrev_b64 v[24:25], 12, v[2:3]
	v_add_co_u32_e32 v8, vcc, s16, v4
	v_lshl_add_u64 v[6:7], v[134:135], 0, v[24:25]
	s_nop 0
	v_addc_co_u32_e32 v9, vcc, 0, v5, vcc
	v_add_co_u32_e32 v10, vcc, s16, v6
	global_load_dwordx4 v[66:69], v[4:5], off
	global_load_dwordx4 v[70:73], v[6:7], off
	v_addc_co_u32_e32 v11, vcc, 0, v7, vcc
	v_add_co_u32_e32 v12, vcc, s17, v4
	global_load_dwordx4 v[74:77], v[8:9], off
	global_load_dwordx4 v[78:81], v[10:11], off
	v_addc_co_u32_e32 v13, vcc, 0, v5, vcc
	v_add_co_u32_e32 v14, vcc, s17, v6
	global_load_dwordx4 v[82:85], v[12:13], off
	s_nop 0
	v_addc_co_u32_e32 v15, vcc, 0, v7, vcc
	v_add_co_u32_e32 v16, vcc, s18, v6
	global_load_dwordx4 v[86:89], v[14:15], off
	s_nop 0
	v_addc_co_u32_e32 v17, vcc, 0, v7, vcc
	v_add_co_u32_e32 v18, vcc, s18, v4
	global_load_dwordx4 v[94:97], v[16:17], off
	s_nop 0
	v_addc_co_u32_e32 v19, vcc, 0, v5, vcc
	global_load_dwordx4 v[90:93], v[18:19], off
	global_load_dwordx4 v[98:101], v[4:5], off offset:128
	global_load_dwordx4 v[102:105], v[6:7], off offset:128
	global_load_dwordx4 v[106:109], v[8:9], off offset:128
	global_load_dwordx4 v[110:113], v[10:11], off offset:128
	global_load_dwordx4 v[114:117], v[12:13], off offset:128
	global_load_dwordx4 v[118:121], v[14:15], off offset:128
	global_load_dwordx4 v[122:125], v[18:19], off offset:128
	global_load_dwordx4 v[126:129], v[16:17], off offset:128
	s_mov_b32 s24, 0
	v_mov_b32_e32 v2, 0
	v_mov_b32_e32 v3, v131
	v_mov_b32_e32 v4, v131
	v_mov_b32_e32 v5, v131
	v_mov_b32_e32 v6, v131
	v_mov_b32_e32 v7, v131
	v_mov_b32_e32 v8, v131
	v_mov_b32_e32 v9, v131
	v_mov_b32_e32 v10, v131
	v_mov_b32_e32 v11, v131
	v_mov_b32_e32 v12, v131
	v_mov_b32_e32 v13, v131
	v_mov_b32_e32 v14, v131
	v_mov_b32_e32 v15, v131
	v_mov_b32_e32 v16, v131
	v_mov_b32_e32 v17, v131
	v_mov_b32_e32 v18, 0
	v_mov_b32_e32 v19, v131
	v_mov_b32_e32 v20, v131
	v_lshl_add_u64 v[138:139], s[82:83], 0, v[24:25]
	v_lshl_add_u64 v[140:141], s[82:83], 0, v[22:23]
	v_add_u32_e32 v190, v24, v136
	v_add_u32_e32 v191, 0x20000, v190
	v_add_u32_e32 v192, 0x40000, v190
	v_add_u32_e32 v193, 0x60000, v190
	s_add_u32 s98, s82, 0xb8000
	s_addc_u32 s99, s83, 0
	v_add_u32_e32 v194, v22, v136
	v_add_u32_e32 v195, 0x20000, v194
	v_add_u32_e32 v196, 0x40000, v194
	v_add_u32_e32 v197, 0x60000, v194
	s_add_u32 s100, s82, 0x6538000
	s_addc_u32 s101, s83, 0
	v_mov_b32_e32 v21, v131
	v_mov_b32_e32 v22, v131
	v_mov_b32_e32 v23, v131
	v_mov_b32_e32 v24, v131
	v_mov_b32_e32 v25, v131
	v_mov_b32_e32 v26, v131
	v_mov_b32_e32 v27, v131
	v_mov_b32_e32 v28, v131
	v_mov_b32_e32 v29, v131
	v_mov_b32_e32 v30, v131
	v_mov_b32_e32 v31, v131
	v_mov_b32_e32 v32, v131
	v_mov_b32_e32 v33, v131
	v_mov_b32_e32 v34, 0
	v_mov_b32_e32 v35, v131
	v_mov_b32_e32 v36, v131
	v_mov_b32_e32 v37, v131
	v_mov_b32_e32 v38, v131
	v_mov_b32_e32 v39, v131
	v_mov_b32_e32 v40, v131
	v_mov_b32_e32 v41, v131
	v_mov_b32_e32 v42, v131
	v_mov_b32_e32 v43, v131
	v_mov_b32_e32 v44, v131
	v_mov_b32_e32 v45, v131
	v_mov_b32_e32 v46, v131
	v_mov_b32_e32 v47, v131
	v_mov_b32_e32 v48, v131
	v_mov_b32_e32 v49, v131
	v_mov_b32_e32 v50, 0
	v_mov_b32_e32 v51, v131
	v_mov_b32_e32 v52, v131
	v_mov_b32_e32 v53, v131
	v_mov_b32_e32 v54, v131
	v_mov_b32_e32 v55, v131
	v_mov_b32_e32 v56, v131
	v_mov_b32_e32 v57, v131
	v_mov_b32_e32 v58, v131
	v_mov_b32_e32 v59, v131
	v_mov_b32_e32 v60, v131
	v_mov_b32_e32 v61, v131
	v_mov_b32_e32 v62, v131
	v_mov_b32_e32 v63, v131
	v_mov_b32_e32 v64, v131
	v_mov_b32_e32 v65, v131
	s_waitcnt lgkmcnt(0)
	s_barrier
	s_waitcnt vmcnt(14)
	ds_write_b128 v146, v[70:73] offset:36880
	ds_write_b128 v146, v[66:69] offset:16
	s_waitcnt vmcnt(12)
	ds_write_b128 v146, v[78:81] offset:41488
	s_waitcnt vmcnt(10)
	ds_write_b128 v146, v[86:89] offset:46096
	s_waitcnt vmcnt(9)
	ds_write_b128 v146, v[94:97] offset:50704
	ds_write_b128 v146, v[74:77] offset:4624
	ds_write_b128 v146, v[82:85] offset:9232
	s_waitcnt vmcnt(8)
	ds_write_b128 v146, v[90:93] offset:13840
	s_waitcnt lgkmcnt(0)
	s_barrier
	s_branch .LBB0_387
; #define MFMA(a, b, c) __builtin_amdgcn_mfma_f32_32x32x16_bf16((a), (b), (c), 0, 0, 0)
; template <bool SWAP, class Epi>
; DI void gemm_tile(const u16* __restrict__ A, int lda, const u16* __restrict__ Bt, int ldb, int K, int m0, int n0, char* smem, Epi&& epi) {
;     ...
;   auto compute = [&](int buf) __attribute__((always_inline)) {
;     bf16x8 af[2][2], bfr[2][2];
;     af[0][0] = *(const bf16x8*)(Asb + buf * 128 * 72);
;     af[0][1] = *(const bf16x8*)(Asb + buf * 128 * 72 + 32 * 72);
;     bfr[0][0] = *(const bf16x8*)(Bsb + buf * 128 * 72);
;     bfr[0][1] = *(const bf16x8*)(Bsb + buf * 128 * 72 + 32 * 72);
; #pragma unroll
;     for (int ks = 0; ks < 4; ++ks) {
;       const int c = ks & 1, n = c ^ 1;
;       if (ks < 3) {
;         af[n][0] = *(const bf16x8*)(Asb + buf * 128 * 72 + (ks + 1) * 16);
;         af[n][1] = *(const bf16x8*)(Asb + buf * 128 * 72 + 32 * 72 + (ks + 1) * 16);
;         bfr[n][0] = *(const bf16x8*)(Bsb + buf * 128 * 72 + (ks + 1) * 16);
;         bfr[n][1] = *(const bf16x8*)(Bsb + buf * 128 * 72 + 32 * 72 + (ks + 1) * 16);
;       }
;       __builtin_amdgcn_sched_barrier(0);
; #pragma unroll
;       for (int mi = 0; mi < 2; ++mi)
; #pragma unroll
;         for (int ni = 0; ni < 2; ++ni) {
;           if (SWAP) acc[mi][ni] = MFMA(bfr[c][ni], af[c][mi], acc[mi][ni]);
;           else acc[mi][ni] = MFMA(af[c][mi], bfr[c][ni], acc[mi][ni]);
;         }
;       __builtin_amdgcn_sched_barrier(0);
;     }
;   };
;   for (int kt = 0; kt < KT; kt += 2) {
;     if (kt + 2 < KT) {
;       const int k0 = (kt + 2) << 6;
; #pragma unroll
;       for (int i = 0; i < 4; ++i) { ra0[i] = *(const u32x4*)(ag + (size_t)i * 32 * lda + k0); rb0[i] = *(const u32x4*)(bg + (size_t)i * 32 * ldb + k0); }
;     }
;     compute(0);
; #pragma unroll
;     for (int i = 0; i < 4; ++i) { *(u32x4*)(asw + 128 * 72 + 32 * i * 72) = ra1[i]; *(u32x4*)(bsw + 128 * 72 + 32 * i * 72) = rb1[i]; }
;     __syncthreads();
;     if (kt + 3 < KT) {
;       const int k0 = (kt + 3) << 6;
; #pragma unroll
;       for (int i = 0; i < 4; ++i) { ra1[i] = *(const u32x4*)(ag + (size_t)i * 32 * lda + k0); rb1[i] = *(const u32x4*)(bg + (size_t)i * 32 * ldb + k0); }
;     }
;     compute(1);
;     if (kt + 2 < KT) {
; #pragma unroll
;       for (int i = 0; i < 4; ++i) { *(u32x4*)(asw + 32 * i * 72) = ra0[i]; *(u32x4*)(bsw + 32 * i * 72) = rb0[i]; }
;     }
;     __syncthreads();
;   }
.LBB0_387:
	global_load_dwordx4 v[66:69], v194, s[100:101] offset:256
	global_load_dwordx4 v[70:73], v190, s[98:99] offset:256
	global_load_dwordx4 v[74:77], v195, s[100:101] offset:256
	global_load_dwordx4 v[78:81], v191, s[98:99] offset:256
	global_load_dwordx4 v[82:85], v196, s[100:101] offset:256
	global_load_dwordx4 v[86:89], v192, s[98:99] offset:256
	global_load_dwordx4 v[90:93], v197, s[100:101] offset:256
	global_load_dwordx4 v[94:97], v193, s[98:99] offset:256
	ds_read_b128 v[154:157], v149 offset:16
	ds_read_b128 v[158:161], v149 offset:48
	ds_read_b128 v[162:165], v149 offset:4624
	ds_read_b128 v[166:169], v149 offset:4656
	ds_read_b128 v[170:173], v150 offset:36880
	ds_read_b128 v[174:177], v150 offset:36912
	ds_read_b128 v[178:181], v150 offset:41488
	ds_read_b128 v[182:185], v150 offset:41520
	s_waitcnt lgkmcnt(3)
	v_mfma_f32_32x32x16_bf16 v[50:65], v[170:173], v[154:157], v[50:65]
	s_waitcnt lgkmcnt(1)
	v_mfma_f32_32x32x16_bf16 v[34:49], v[178:181], v[154:157], v[34:49]
	v_mfma_f32_32x32x16_bf16 v[18:33], v[170:173], v[162:165], v[18:33]
	v_mfma_f32_32x32x16_bf16 v[2:17], v[178:181], v[162:165], v[2:17]
	ds_read_b128 v[154:157], v149 offset:80
	ds_read_b128 v[162:165], v149 offset:4688
	ds_read_b128 v[170:173], v150 offset:36944
	ds_read_b128 v[178:181], v150 offset:41552
	v_mfma_f32_32x32x16_bf16 v[50:65], v[174:177], v[158:161], v[50:65]
	s_waitcnt lgkmcnt(4)
	v_mfma_f32_32x32x16_bf16 v[34:49], v[182:185], v[158:161], v[34:49]
	v_mfma_f32_32x32x16_bf16 v[18:33], v[174:177], v[166:169], v[18:33]
	v_mfma_f32_32x32x16_bf16 v[2:17], v[182:185], v[166:169], v[2:17]
	ds_read_b128 v[158:161], v149 offset:112
	ds_read_b128 v[166:169], v149 offset:4720
	ds_read_b128 v[174:177], v150 offset:36976
	ds_read_b128 v[182:185], v150 offset:41584
	s_waitcnt lgkmcnt(5)
	v_mfma_f32_32x32x16_bf16 v[50:65], v[170:173], v[154:157], v[50:65]
	s_waitcnt vmcnt(14)
	ds_write_b128 v146, v[98:101] offset:18448
	ds_write_b128 v146, v[102:105] offset:55312
	s_waitcnt lgkmcnt(6)
	v_mfma_f32_32x32x16_bf16 v[34:49], v[178:181], v[154:157], v[34:49]
	v_mfma_f32_32x32x16_bf16 v[18:33], v[170:173], v[162:165], v[18:33]
	s_waitcnt vmcnt(12)
	ds_write_b128 v146, v[106:109] offset:23056
	ds_write_b128 v146, v[110:113] offset:59920
	v_mfma_f32_32x32x16_bf16 v[2:17], v[178:181], v[162:165], v[2:17]
	s_waitcnt vmcnt(10)
	ds_write_b128 v146, v[114:117] offset:27664
	ds_write_b128 v146, v[118:121] offset:64528
	s_waitcnt lgkmcnt(7)
	v_mfma_f32_32x32x16_bf16 v[50:65], v[174:177], v[158:161], v[50:65]
	s_waitcnt vmcnt(8)
	ds_write_b128 v146, v[122:125] offset:32272
	ds_write_b128 v147, v[126:129] offset:32256
	s_waitcnt lgkmcnt(8)
	v_mfma_f32_32x32x16_bf16 v[34:49], v[182:185], v[158:161], v[34:49]
	v_mfma_f32_32x32x16_bf16 v[18:33], v[174:177], v[166:169], v[18:33]
	v_mfma_f32_32x32x16_bf16 v[2:17], v[182:185], v[166:169], v[2:17]
	s_waitcnt lgkmcnt(0)
	s_barrier
	global_load_dwordx4 v[98:101], v194, s[100:101] offset:384
	global_load_dwordx4 v[102:105], v190, s[98:99] offset:384
	global_load_dwordx4 v[106:109], v195, s[100:101] offset:384
	global_load_dwordx4 v[110:113], v191, s[98:99] offset:384
	global_load_dwordx4 v[114:117], v196, s[100:101] offset:384
	global_load_dwordx4 v[118:121], v192, s[98:99] offset:384
	global_load_dwordx4 v[122:125], v197, s[100:101] offset:384
	global_load_dwordx4 v[126:129], v193, s[98:99] offset:384
	ds_read_b128 v[142:145], v149 offset:18448
	ds_read_b128 v[154:157], v149 offset:18480
	ds_read_b128 v[158:161], v149 offset:23056
	ds_read_b128 v[162:165], v149 offset:23088
	ds_read_b128 v[166:169], v150 offset:55312
	ds_read_b128 v[170:173], v150 offset:55344
	ds_read_b128 v[174:177], v150 offset:59920
	ds_read_b128 v[178:181], v150 offset:59952
	s_waitcnt lgkmcnt(3)
	v_mfma_f32_32x32x16_bf16 v[50:65], v[166:169], v[142:145], v[50:65]
	s_waitcnt lgkmcnt(1)
	v_mfma_f32_32x32x16_bf16 v[34:49], v[174:177], v[142:145], v[34:49]
	v_mfma_f32_32x32x16_bf16 v[18:33], v[166:169], v[158:161], v[18:33]
	v_mfma_f32_32x32x16_bf16 v[2:17], v[174:177], v[158:161], v[2:17]
	ds_read_b128 v[142:145], v149 offset:18512
	ds_read_b128 v[158:161], v149 offset:23120
	ds_read_b128 v[166:169], v150 offset:55376
	ds_read_b128 v[174:177], v150 offset:59984
	v_mfma_f32_32x32x16_bf16 v[50:65], v[170:173], v[154:157], v[50:65]
	s_waitcnt lgkmcnt(4)
	v_mfma_f32_32x32x16_bf16 v[34:49], v[178:181], v[154:157], v[34:49]
	v_mfma_f32_32x32x16_bf16 v[18:33], v[170:173], v[162:165], v[18:33]
	v_mfma_f32_32x32x16_bf16 v[2:17], v[178:181], v[162:165], v[2:17]
	ds_read_b128 v[154:157], v149 offset:18544
	ds_read_b128 v[162:165], v149 offset:23152
	ds_read_b128 v[170:173], v150 offset:55408
	ds_read_b128 v[178:181], v150 offset:60016
	s_waitcnt lgkmcnt(5)
	v_mfma_f32_32x32x16_bf16 v[50:65], v[166:169], v[142:145], v[50:65]
	s_waitcnt vmcnt(14)
	ds_write_b128 v146, v[66:69] offset:16
	ds_write_b128 v146, v[70:73] offset:36880
	s_waitcnt lgkmcnt(6)
	v_mfma_f32_32x32x16_bf16 v[34:49], v[174:177], v[142:145], v[34:49]
	v_mfma_f32_32x32x16_bf16 v[18:33], v[166:169], v[158:161], v[18:33]
	s_waitcnt vmcnt(12)
	ds_write_b128 v146, v[74:77] offset:4624
	ds_write_b128 v146, v[78:81] offset:41488
	v_mfma_f32_32x32x16_bf16 v[2:17], v[174:177], v[158:161], v[2:17]
	s_waitcnt vmcnt(10)
	ds_write_b128 v146, v[82:85] offset:9232
	ds_write_b128 v146, v[86:89] offset:46096
	s_waitcnt lgkmcnt(7)
	v_mfma_f32_32x32x16_bf16 v[50:65], v[170:173], v[154:157], v[50:65]
	s_waitcnt vmcnt(8)
	ds_write_b128 v146, v[90:93] offset:13840
	ds_write_b128 v146, v[94:97] offset:50704
	s_waitcnt lgkmcnt(8)
	v_mfma_f32_32x32x16_bf16 v[34:49], v[178:181], v[154:157], v[34:49]
	v_mfma_f32_32x32x16_bf16 v[18:33], v[170:173], v[162:165], v[18:33]
	v_mfma_f32_32x32x16_bf16 v[2:17], v[178:181], v[162:165], v[2:17]
	s_add_i32 s24, s24, 2
	s_add_u32 s98, s98, 256
	s_addc_u32 s99, s99, 0
	s_add_u32 s100, s100, 256
	s_addc_u32 s101, s101, 0
	s_waitcnt lgkmcnt(0)
	s_barrier
; #define MFMA(a, b, c) __builtin_amdgcn_mfma_f32_32x32x16_bf16((a), (b), (c), 0, 0, 0)
; template <bool SWAP, class Epi>
; DI void gemm_tile(const u16* __restrict__ A, int lda, const u16* __restrict__ Bt, int ldb, int K, int m0, int n0, char* smem, Epi&& epi) {
;     ...
;   auto compute = [&](int buf) __attribute__((always_inline)) {
;     bf16x8 af[2][2], bfr[2][2];
;     af[0][0] = *(const bf16x8*)(Asb + buf * 128 * 72);
;     af[0][1] = *(const bf16x8*)(Asb + buf * 128 * 72 + 32 * 72);
;     bfr[0][0] = *(const bf16x8*)(Bsb + buf * 128 * 72);
;     bfr[0][1] = *(const bf16x8*)(Bsb + buf * 128 * 72 + 32 * 72);
; #pragma unroll
;     for (int ks = 0; ks < 4; ++ks) {
;       const int c = ks & 1, n = c ^ 1;
;       if (ks < 3) {
;         af[n][0] = *(const bf16x8*)(Asb + buf * 128 * 72 + (ks + 1) * 16);
;         af[n][1] = *(const bf16x8*)(Asb + buf * 128 * 72 + 32 * 72 + (ks + 1) * 16);
;         bfr[n][0] = *(const bf16x8*)(Bsb + buf * 128 * 72 + (ks + 1) * 16);
;         bfr[n][1] = *(const bf16x8*)(Bsb + buf * 128 * 72 + 32 * 72 + (ks + 1) * 16);
;       }
;       __builtin_amdgcn_sched_barrier(0);
; #pragma unroll
;       for (int mi = 0; mi < 2; ++mi)
; #pragma unroll
;         for (int ni = 0; ni < 2; ++ni) {
;           if (SWAP) acc[mi][ni] = MFMA(bfr[c][ni], af[c][mi], acc[mi][ni]);
;           else acc[mi][ni] = MFMA(af[c][mi], bfr[c][ni], acc[mi][ni]);
;         }
;       __builtin_amdgcn_sched_barrier(0);
;     }
;   };
;   for (int kt = 0; kt < KT; kt += 2) {
;     if (kt + 2 < KT) {
;       const int k0 = (kt + 2) << 6;
; #pragma unroll
;       for (int i = 0; i < 4; ++i) { ra0[i] = *(const u32x4*)(ag + (size_t)i * 32 * lda + k0); rb0[i] = *(const u32x4*)(bg + (size_t)i * 32 * ldb + k0); }
;     }
;     compute(0);
; #pragma unroll
;     for (int i = 0; i < 4; ++i) { *(u32x4*)(asw + 128 * 72 + 32 * i * 72) = ra1[i]; *(u32x4*)(bsw + 128 * 72 + 32 * i * 72) = rb1[i]; }
;     __syncthreads();
;     if (kt + 3 < KT) {
;       const int k0 = (kt + 3) << 6;
; #pragma unroll
;       for (int i = 0; i < 4; ++i) { ra1[i] = *(const u32x4*)(ag + (size_t)i * 32 * lda + k0); rb1[i] = *(const u32x4*)(bg + (size_t)i * 32 * ldb + k0); }
;     }
;     compute(1);
;     if (kt + 2 < KT) {
; #pragma unroll
;       for (int i = 0; i < 4; ++i) { *(u32x4*)(asw + 32 * i * 72) = ra0[i]; *(u32x4*)(bsw + 32 * i * 72) = rb0[i]; }
;     }
;     __syncthreads();
;   }
	s_cmp_lt_u32 s24, 30
	s_cbranch_scc1 .LBB0_387
	ds_read_b128 v[154:157], v149 offset:16
	ds_read_b128 v[158:161], v149 offset:48
	ds_read_b128 v[162:165], v149 offset:4624
	ds_read_b128 v[166:169], v149 offset:4656
	ds_read_b128 v[170:173], v150 offset:36880
	ds_read_b128 v[174:177], v150 offset:36912
	ds_read_b128 v[178:181], v150 offset:41488
	ds_read_b128 v[182:185], v150 offset:41520
	s_waitcnt lgkmcnt(3)
	v_mfma_f32_32x32x16_bf16 v[50:65], v[170:173], v[154:157], v[50:65]
	s_waitcnt lgkmcnt(1)
	v_mfma_f32_32x32x16_bf16 v[34:49], v[178:181], v[154:157], v[34:49]
	v_mfma_f32_32x32x16_bf16 v[18:33], v[170:173], v[162:165], v[18:33]
	v_mfma_f32_32x32x16_bf16 v[2:17], v[178:181], v[162:165], v[2:17]
	ds_read_b128 v[154:157], v149 offset:80
	ds_read_b128 v[162:165], v149 offset:4688
	ds_read_b128 v[170:173], v150 offset:36944
	ds_read_b128 v[178:181], v150 offset:41552
	v_mfma_f32_32x32x16_bf16 v[50:65], v[174:177], v[158:161], v[50:65]
	s_waitcnt lgkmcnt(4)
	v_mfma_f32_32x32x16_bf16 v[34:49], v[182:185], v[158:161], v[34:49]
	v_mfma_f32_32x32x16_bf16 v[18:33], v[174:177], v[166:169], v[18:33]
	v_mfma_f32_32x32x16_bf16 v[2:17], v[182:185], v[166:169], v[2:17]
	ds_read_b128 v[158:161], v149 offset:112
	ds_read_b128 v[166:169], v149 offset:4720
	ds_read_b128 v[174:177], v150 offset:36976
	ds_read_b128 v[182:185], v150 offset:41584
	s_waitcnt lgkmcnt(5)
	v_mfma_f32_32x32x16_bf16 v[50:65], v[170:173], v[154:157], v[50:65]
	s_waitcnt vmcnt(6)
	ds_write_b128 v146, v[98:101] offset:18448
	ds_write_b128 v146, v[102:105] offset:55312
	s_waitcnt lgkmcnt(6)
	v_mfma_f32_32x32x16_bf16 v[34:49], v[178:181], v[154:157], v[34:49]
	v_mfma_f32_32x32x16_bf16 v[18:33], v[170:173], v[162:165], v[18:33]
	s_waitcnt vmcnt(4)
	ds_write_b128 v146, v[106:109] offset:23056
	ds_write_b128 v146, v[110:113] offset:59920
	v_mfma_f32_32x32x16_bf16 v[2:17], v[178:181], v[162:165], v[2:17]
	s_waitcnt vmcnt(2)
	ds_write_b128 v146, v[114:117] offset:27664
	ds_write_b128 v146, v[118:121] offset:64528
	s_waitcnt lgkmcnt(7)
	v_mfma_f32_32x32x16_bf16 v[50:65], v[174:177], v[158:161], v[50:65]
	s_waitcnt vmcnt(0)
	ds_write_b128 v146, v[122:125] offset:32272
	ds_write_b128 v147, v[126:129] offset:32256
	s_waitcnt lgkmcnt(8)
	v_mfma_f32_32x32x16_bf16 v[34:49], v[182:185], v[158:161], v[34:49]
	v_mfma_f32_32x32x16_bf16 v[18:33], v[174:177], v[166:169], v[18:33]
	v_mfma_f32_32x32x16_bf16 v[2:17], v[182:185], v[166:169], v[2:17]
	s_waitcnt lgkmcnt(0)
	s_barrier
	ds_read_b128 v[142:145], v149 offset:18448
	ds_read_b128 v[154:157], v149 offset:18480
	ds_read_b128 v[158:161], v149 offset:23056
	ds_read_b128 v[162:165], v149 offset:23088
	ds_read_b128 v[166:169], v150 offset:55312
	ds_read_b128 v[170:173], v150 offset:55344
	ds_read_b128 v[174:177], v150 offset:59920
	ds_read_b128 v[178:181], v150 offset:59952
	s_waitcnt lgkmcnt(3)
	v_mfma_f32_32x32x16_bf16 v[50:65], v[166:169], v[142:145], v[50:65]
	s_waitcnt lgkmcnt(1)
	v_mfma_f32_32x32x16_bf16 v[34:49], v[174:177], v[142:145], v[34:49]
	v_mfma_f32_32x32x16_bf16 v[18:33], v[166:169], v[158:161], v[18:33]
	v_mfma_f32_32x32x16_bf16 v[2:17], v[174:177], v[158:161], v[2:17]
	ds_read_b128 v[142:145], v149 offset:18512
	ds_read_b128 v[158:161], v149 offset:23120
	ds_read_b128 v[166:169], v150 offset:55376
	ds_read_b128 v[174:177], v150 offset:59984
	v_mfma_f32_32x32x16_bf16 v[50:65], v[170:173], v[154:157], v[50:65]
	s_waitcnt lgkmcnt(4)
	v_mfma_f32_32x32x16_bf16 v[34:49], v[178:181], v[154:157], v[34:49]
	v_mfma_f32_32x32x16_bf16 v[18:33], v[170:173], v[162:165], v[18:33]
	v_mfma_f32_32x32x16_bf16 v[2:17], v[178:181], v[162:165], v[2:17]
	ds_read_b128 v[154:157], v149 offset:18544
	ds_read_b128 v[162:165], v149 offset:23152
	ds_read_b128 v[170:173], v150 offset:55408
	ds_read_b128 v[178:181], v150 offset:60016
	s_waitcnt lgkmcnt(5)
	v_mfma_f32_32x32x16_bf16 v[50:65], v[166:169], v[142:145], v[50:65]
	s_waitcnt lgkmcnt(4)
	v_mfma_f32_32x32x16_bf16 v[34:49], v[174:177], v[142:145], v[34:49]
	v_mfma_f32_32x32x16_bf16 v[18:33], v[166:169], v[158:161], v[18:33]
	v_mfma_f32_32x32x16_bf16 v[2:17], v[174:177], v[158:161], v[2:17]
	s_waitcnt lgkmcnt(1)
	v_mfma_f32_32x32x16_bf16 v[50:65], v[170:173], v[154:157], v[50:65]
	s_waitcnt lgkmcnt(0)
	v_mfma_f32_32x32x16_bf16 v[34:49], v[178:181], v[154:157], v[34:49]
	v_mfma_f32_32x32x16_bf16 v[18:33], v[170:173], v[162:165], v[18:33]
	v_mfma_f32_32x32x16_bf16 v[2:17], v[178:181], v[162:165], v[2:17]
	s_waitcnt lgkmcnt(0)
	s_barrier
	s_branch .LBB0_393

; template <bool SWAP, class Epi>
; DI void gemm_tile(const u16* __restrict__ A, int lda, const u16* __restrict__ Bt, int ldb, int K, int m0, int n0, char* smem, Epi&& epi) {
;   u16* As = (u16*)(smem + 16);
;   u16* Bs = As + 2 * 128 * 72;
;   const int tid = threadIdx.x, lane = tid & 63, w = tid >> 6, wm = w >> 1, wn = w & 1;
;   const int r = lane & 31, hi = lane >> 5;
;   f32x16 acc[2][2];
; #pragma unroll
;   for (int a = 0; a < 2; ++a)
; #pragma unroll
;     for (int b = 0; b < 2; ++b)
; #pragma unroll
;       for (int i = 0; i < 16; ++i) acc[a][b][i] = 0.f;
;   const int srow = tid >> 3, skc = tid & 7;
;   const u16* ag = A + (size_t)(m0 + srow) * lda + skc * 8;
;   const u16* bg = Bt + (size_t)(n0 + srow) * ldb + skc * 8;
;   u16* asw = As + srow * 72 + skc * 8;
;   u16* bsw = Bs + srow * 72 + skc * 8;
;   u32x4 ra0[4], rb0[4], ra1[4], rb1[4];
; #pragma unroll
;   for (int i = 0; i < 4; ++i) { ra0[i] = *(const u32x4*)(ag + (size_t)i * 32 * lda); rb0[i] = *(const u32x4*)(bg + (size_t)i * 32 * ldb); }
; #pragma unroll
;   for (int i = 0; i < 4; ++i) { ra1[i] = *(const u32x4*)(ag + (size_t)i * 32 * lda + 64); rb1[i] = *(const u32x4*)(bg + (size_t)i * 32 * ldb + 64); }
;   __syncthreads();
; #pragma unroll
;   for (int i = 0; i < 4; ++i) { *(u32x4*)(asw + 32 * i * 72) = ra0[i]; *(u32x4*)(bsw + 32 * i * 72) = rb0[i]; }
;   __syncthreads();
;   const int KT = K >> 6;
;   const u16* Asb = As + (wm * 64 + r) * 72 + hi * 8;
;   const u16* Bsb = Bs + (wn * 64 + r) * 72 + hi * 8;
.LBB0_746:
	s_ashr_i32 s8, s17, 31
	s_lshr_b32 s8, s8, 26
	s_add_i32 s8, s17, s8
	s_and_b32 s9, s8, 0x1ffffc0
	s_sub_i32 s9, s17, s9
	s_lshl_b32 s18, s9, 7
	s_lshl_b32 s8, s8, 1
	v_or_b32_e32 v2, s18, v1
	s_and_b32 s19, s8, 0xffffff80
	v_ashrrev_i32_e32 v3, 31, v2
	v_lshlrev_b64 v[22:23], 12, v[2:3]
	v_or_b32_e32 v2, s19, v1
	v_lshl_add_u64 v[4:5], v[132:133], 0, v[22:23]
	v_ashrrev_i32_e32 v3, 31, v2
	v_lshlrev_b64 v[24:25], 12, v[2:3]
	v_add_co_u32_e32 v8, vcc, s14, v4
	v_lshl_add_u64 v[6:7], v[134:135], 0, v[24:25]
	s_nop 0
	v_addc_co_u32_e32 v9, vcc, 0, v5, vcc
	v_add_co_u32_e32 v10, vcc, s14, v6
	global_load_dwordx4 v[66:69], v[4:5], off
	global_load_dwordx4 v[70:73], v[6:7], off
	v_addc_co_u32_e32 v11, vcc, 0, v7, vcc
	v_add_co_u32_e32 v12, vcc, s15, v4
	global_load_dwordx4 v[74:77], v[8:9], off
	global_load_dwordx4 v[78:81], v[10:11], off
	v_addc_co_u32_e32 v13, vcc, 0, v5, vcc
	v_add_co_u32_e32 v14, vcc, s15, v6
	global_load_dwordx4 v[82:85], v[12:13], off
	s_nop 0
	v_addc_co_u32_e32 v15, vcc, 0, v7, vcc
	v_add_co_u32_e32 v16, vcc, s16, v6
	global_load_dwordx4 v[86:89], v[14:15], off
	s_nop 0
	v_addc_co_u32_e32 v17, vcc, 0, v7, vcc
	v_add_co_u32_e32 v18, vcc, s16, v4
	global_load_dwordx4 v[94:97], v[16:17], off
	s_nop 0
	v_addc_co_u32_e32 v19, vcc, 0, v5, vcc
	global_load_dwordx4 v[90:93], v[18:19], off
	global_load_dwordx4 v[98:101], v[4:5], off offset:128
	global_load_dwordx4 v[102:105], v[6:7], off offset:128
	global_load_dwordx4 v[106:109], v[8:9], off offset:128
	global_load_dwordx4 v[110:113], v[10:11], off offset:128
	global_load_dwordx4 v[114:117], v[12:13], off offset:128
	global_load_dwordx4 v[118:121], v[14:15], off offset:128
	global_load_dwordx4 v[122:125], v[18:19], off offset:128
	global_load_dwordx4 v[126:129], v[16:17], off offset:128
	s_mov_b32 s20, 0
	v_mov_b32_e32 v2, 0
	v_mov_b32_e32 v3, v131
	v_mov_b32_e32 v4, v131
	v_mov_b32_e32 v5, v131
	v_mov_b32_e32 v6, v131
	v_mov_b32_e32 v7, v131
	v_mov_b32_e32 v8, v131
	v_mov_b32_e32 v9, v131
	v_mov_b32_e32 v10, v131
	v_mov_b32_e32 v11, v131
	v_mov_b32_e32 v12, v131
	v_mov_b32_e32 v13, v131
	v_mov_b32_e32 v14, v131
	v_mov_b32_e32 v15, v131
	v_mov_b32_e32 v16, v131
	v_mov_b32_e32 v17, v131
	v_mov_b32_e32 v18, 0
	v_mov_b32_e32 v19, v131
	v_mov_b32_e32 v20, v131
	v_lshl_add_u64 v[136:137], s[82:83], 0, v[24:25]
	v_lshl_add_u64 v[138:139], s[82:83], 0, v[22:23]
	v_add_u32_e32 v190, v24, v130
	v_add_u32_e32 v191, 0x20000, v190
	v_add_u32_e32 v192, 0x40000, v190
	v_add_u32_e32 v193, 0x60000, v190
	s_add_u32 s98, s82, 0x14b8000
	s_addc_u32 s99, s83, 0
	v_add_u32_e32 v194, v22, v130
	v_add_u32_e32 v195, 0x20000, v194
	v_add_u32_e32 v196, 0x40000, v194
	v_add_u32_e32 v197, 0x60000, v194
	s_add_u32 s100, s82, 0x10638000
	s_addc_u32 s101, s83, 0
	v_mov_b32_e32 v21, v131
	v_mov_b32_e32 v22, v131
	v_mov_b32_e32 v23, v131
	v_mov_b32_e32 v24, v131
	v_mov_b32_e32 v25, v131
	v_mov_b32_e32 v26, v131
	v_mov_b32_e32 v27, v131
	v_mov_b32_e32 v28, v131
	v_mov_b32_e32 v29, v131
	v_mov_b32_e32 v30, v131
	v_mov_b32_e32 v31, v131
	v_mov_b32_e32 v32, v131
	v_mov_b32_e32 v33, v131
	v_mov_b32_e32 v34, 0
	v_mov_b32_e32 v35, v131
	v_mov_b32_e32 v36, v131
	v_mov_b32_e32 v37, v131
	v_mov_b32_e32 v38, v131
	v_mov_b32_e32 v39, v131
	v_mov_b32_e32 v40, v131
	v_mov_b32_e32 v41, v131
	v_mov_b32_e32 v42, v131
	v_mov_b32_e32 v43, v131
	v_mov_b32_e32 v44, v131
	v_mov_b32_e32 v45, v131
	v_mov_b32_e32 v46, v131
	v_mov_b32_e32 v47, v131
	v_mov_b32_e32 v48, v131
	v_mov_b32_e32 v49, v131
	v_mov_b32_e32 v50, 0
	v_mov_b32_e32 v51, v131
	v_mov_b32_e32 v52, v131
	v_mov_b32_e32 v53, v131
	v_mov_b32_e32 v54, v131
	v_mov_b32_e32 v55, v131
	v_mov_b32_e32 v56, v131
	v_mov_b32_e32 v57, v131
	v_mov_b32_e32 v58, v131
	v_mov_b32_e32 v59, v131
	v_mov_b32_e32 v60, v131
	v_mov_b32_e32 v61, v131
	v_mov_b32_e32 v62, v131
	v_mov_b32_e32 v63, v131
	v_mov_b32_e32 v64, v131
	v_mov_b32_e32 v65, v131
	s_waitcnt lgkmcnt(0)
	s_barrier
	s_waitcnt vmcnt(14)
	ds_write_b128 v144, v[70:73] offset:36880
	ds_write_b128 v144, v[66:69] offset:16
	s_waitcnt vmcnt(12)
	ds_write_b128 v144, v[78:81] offset:41488
	s_waitcnt vmcnt(10)
	ds_write_b128 v144, v[86:89] offset:46096
	s_waitcnt vmcnt(9)
	ds_write_b128 v144, v[94:97] offset:50704
	ds_write_b128 v144, v[74:77] offset:4624
	ds_write_b128 v144, v[82:85] offset:9232
	s_waitcnt vmcnt(8)
	ds_write_b128 v144, v[90:93] offset:13840
	s_waitcnt lgkmcnt(0)
	s_barrier
	s_branch .LBB0_748
; #define MFMA(a, b, c) __builtin_amdgcn_mfma_f32_32x32x16_bf16((a), (b), (c), 0, 0, 0)
; template <bool SWAP, class Epi>
; DI void gemm_tile(const u16* __restrict__ A, int lda, const u16* __restrict__ Bt, int ldb, int K, int m0, int n0, char* smem, Epi&& epi) {
;     ...
;   auto compute = [&](int buf) __attribute__((always_inline)) {
;     bf16x8 af[2][2], bfr[2][2];
;     af[0][0] = *(const bf16x8*)(Asb + buf * 128 * 72);
;     af[0][1] = *(const bf16x8*)(Asb + buf * 128 * 72 + 32 * 72);
;     bfr[0][0] = *(const bf16x8*)(Bsb + buf * 128 * 72);
;     bfr[0][1] = *(const bf16x8*)(Bsb + buf * 128 * 72 + 32 * 72);
; #pragma unroll
;     for (int ks = 0; ks < 4; ++ks) {
;       const int c = ks & 1, n = c ^ 1;
;       if (ks < 3) {
;         af[n][0] = *(const bf16x8*)(Asb + buf * 128 * 72 + (ks + 1) * 16);
;         af[n][1] = *(const bf16x8*)(Asb + buf * 128 * 72 + 32 * 72 + (ks + 1) * 16);
;         bfr[n][0] = *(const bf16x8*)(Bsb + buf * 128 * 72 + (ks + 1) * 16);
;         bfr[n][1] = *(const bf16x8*)(Bsb + buf * 128 * 72 + 32 * 72 + (ks + 1) * 16);
;       }
;       __builtin_amdgcn_sched_barrier(0);
; #pragma unroll
;       for (int mi = 0; mi < 2; ++mi)
; #pragma unroll
;         for (int ni = 0; ni < 2; ++ni) {
;           if (SWAP) acc[mi][ni] = MFMA(bfr[c][ni], af[c][mi], acc[mi][ni]);
;           else acc[mi][ni] = MFMA(af[c][mi], bfr[c][ni], acc[mi][ni]);
;         }
;       __builtin_amdgcn_sched_barrier(0);
;     }
;   };
;   for (int kt = 0; kt < KT; kt += 2) {
;     if (kt + 2 < KT) {
;       const int k0 = (kt + 2) << 6;
; #pragma unroll
;       for (int i = 0; i < 4; ++i) { ra0[i] = *(const u32x4*)(ag + (size_t)i * 32 * lda + k0); rb0[i] = *(const u32x4*)(bg + (size_t)i * 32 * ldb + k0); }
;     }
;     compute(0);
; #pragma unroll
;     for (int i = 0; i < 4; ++i) { *(u32x4*)(asw + 128 * 72 + 32 * i * 72) = ra1[i]; *(u32x4*)(bsw + 128 * 72 + 32 * i * 72) = rb1[i]; }
;     __syncthreads();
;     if (kt + 3 < KT) {
;       const int k0 = (kt + 3) << 6;
; #pragma unroll
;       for (int i = 0; i < 4; ++i) { ra1[i] = *(const u32x4*)(ag + (size_t)i * 32 * lda + k0); rb1[i] = *(const u32x4*)(bg + (size_t)i * 32 * ldb + k0); }
;     }
;     compute(1);
;     if (kt + 2 < KT) {
; #pragma unroll
;       for (int i = 0; i < 4; ++i) { *(u32x4*)(asw + 32 * i * 72) = ra0[i]; *(u32x4*)(bsw + 32 * i * 72) = rb0[i]; }
;     }
;     __syncthreads();
;   }
.LBB0_748:
	global_load_dwordx4 v[66:69], v194, s[100:101] offset:256
	global_load_dwordx4 v[70:73], v190, s[98:99] offset:256
	global_load_dwordx4 v[74:77], v195, s[100:101] offset:256
	global_load_dwordx4 v[78:81], v191, s[98:99] offset:256
	global_load_dwordx4 v[82:85], v196, s[100:101] offset:256
	global_load_dwordx4 v[86:89], v192, s[98:99] offset:256
	global_load_dwordx4 v[90:93], v197, s[100:101] offset:256
	global_load_dwordx4 v[94:97], v193, s[98:99] offset:256
	ds_read_b128 v[150:153], v147 offset:16
	ds_read_b128 v[154:157], v147 offset:48
	ds_read_b128 v[158:161], v147 offset:4624
	ds_read_b128 v[162:165], v147 offset:4656
	ds_read_b128 v[166:169], v148 offset:36880
	ds_read_b128 v[170:173], v148 offset:36912
	ds_read_b128 v[174:177], v148 offset:41488
	ds_read_b128 v[178:181], v148 offset:41520
	s_waitcnt lgkmcnt(3)
	v_mfma_f32_32x32x16_bf16 v[50:65], v[166:169], v[150:153], v[50:65]
	s_waitcnt lgkmcnt(1)
	v_mfma_f32_32x32x16_bf16 v[34:49], v[174:177], v[150:153], v[34:49]
	v_mfma_f32_32x32x16_bf16 v[18:33], v[166:169], v[158:161], v[18:33]
	v_mfma_f32_32x32x16_bf16 v[2:17], v[174:177], v[158:161], v[2:17]
	ds_read_b128 v[150:153], v147 offset:80
	ds_read_b128 v[158:161], v147 offset:4688
	ds_read_b128 v[166:169], v148 offset:36944
	ds_read_b128 v[174:177], v148 offset:41552
	v_mfma_f32_32x32x16_bf16 v[50:65], v[170:173], v[154:157], v[50:65]
	s_waitcnt lgkmcnt(4)
	v_mfma_f32_32x32x16_bf16 v[34:49], v[178:181], v[154:157], v[34:49]
	v_mfma_f32_32x32x16_bf16 v[18:33], v[170:173], v[162:165], v[18:33]
	v_mfma_f32_32x32x16_bf16 v[2:17], v[178:181], v[162:165], v[2:17]
	ds_read_b128 v[154:157], v147 offset:112
	ds_read_b128 v[162:165], v147 offset:4720
	ds_read_b128 v[170:173], v148 offset:36976
	ds_read_b128 v[178:181], v148 offset:41584
	s_waitcnt lgkmcnt(5)
	v_mfma_f32_32x32x16_bf16 v[50:65], v[166:169], v[150:153], v[50:65]
	s_waitcnt vmcnt(14)
	ds_write_b128 v144, v[98:101] offset:18448
	ds_write_b128 v144, v[102:105] offset:55312
	s_waitcnt lgkmcnt(6)
	v_mfma_f32_32x32x16_bf16 v[34:49], v[174:177], v[150:153], v[34:49]
	v_mfma_f32_32x32x16_bf16 v[18:33], v[166:169], v[158:161], v[18:33]
	s_waitcnt vmcnt(12)
	ds_write_b128 v144, v[106:109] offset:23056
	ds_write_b128 v144, v[110:113] offset:59920
	v_mfma_f32_32x32x16_bf16 v[2:17], v[174:177], v[158:161], v[2:17]
	s_waitcnt vmcnt(10)
	ds_write_b128 v144, v[114:117] offset:27664
	ds_write_b128 v144, v[118:121] offset:64528
	s_waitcnt lgkmcnt(7)
	v_mfma_f32_32x32x16_bf16 v[50:65], v[170:173], v[154:157], v[50:65]
	s_waitcnt vmcnt(8)
	ds_write_b128 v144, v[122:125] offset:32272
	ds_write_b128 v145, v[126:129] offset:32256
	s_waitcnt lgkmcnt(8)
	v_mfma_f32_32x32x16_bf16 v[34:49], v[178:181], v[154:157], v[34:49]
	v_mfma_f32_32x32x16_bf16 v[18:33], v[170:173], v[162:165], v[18:33]
	v_mfma_f32_32x32x16_bf16 v[2:17], v[178:181], v[162:165], v[2:17]
	s_waitcnt lgkmcnt(0)
	s_barrier
	global_load_dwordx4 v[98:101], v194, s[100:101] offset:384
	global_load_dwordx4 v[102:105], v190, s[98:99] offset:384
	global_load_dwordx4 v[106:109], v195, s[100:101] offset:384
	global_load_dwordx4 v[110:113], v191, s[98:99] offset:384
	global_load_dwordx4 v[114:117], v196, s[100:101] offset:384
	global_load_dwordx4 v[118:121], v192, s[98:99] offset:384
	global_load_dwordx4 v[122:125], v197, s[100:101] offset:384
	global_load_dwordx4 v[126:129], v193, s[98:99] offset:384
	ds_read_b128 v[140:143], v147 offset:18448
	ds_read_b128 v[150:153], v147 offset:18480
	ds_read_b128 v[154:157], v147 offset:23056
	ds_read_b128 v[158:161], v147 offset:23088
	ds_read_b128 v[162:165], v148 offset:55312
	ds_read_b128 v[166:169], v148 offset:55344
	ds_read_b128 v[170:173], v148 offset:59920
	ds_read_b128 v[174:177], v148 offset:59952
	s_waitcnt lgkmcnt(3)
	v_mfma_f32_32x32x16_bf16 v[50:65], v[162:165], v[140:143], v[50:65]
	s_waitcnt lgkmcnt(1)
	v_mfma_f32_32x32x16_bf16 v[34:49], v[170:173], v[140:143], v[34:49]
	v_mfma_f32_32x32x16_bf16 v[18:33], v[162:165], v[154:157], v[18:33]
	v_mfma_f32_32x32x16_bf16 v[2:17], v[170:173], v[154:157], v[2:17]
	ds_read_b128 v[140:143], v147 offset:18512
	ds_read_b128 v[154:157], v147 offset:23120
	ds_read_b128 v[162:165], v148 offset:55376
	ds_read_b128 v[170:173], v148 offset:59984
	v_mfma_f32_32x32x16_bf16 v[50:65], v[166:169], v[150:153], v[50:65]
	s_waitcnt lgkmcnt(4)
	v_mfma_f32_32x32x16_bf16 v[34:49], v[174:177], v[150:153], v[34:49]
	v_mfma_f32_32x32x16_bf16 v[18:33], v[166:169], v[158:161], v[18:33]
	v_mfma_f32_32x32x16_bf16 v[2:17], v[174:177], v[158:161], v[2:17]
	ds_read_b128 v[150:153], v147 offset:18544
	ds_read_b128 v[158:161], v147 offset:23152
	ds_read_b128 v[166:169], v148 offset:55408
	ds_read_b128 v[174:177], v148 offset:60016
	s_waitcnt lgkmcnt(5)
	v_mfma_f32_32x32x16_bf16 v[50:65], v[162:165], v[140:143], v[50:65]
	s_waitcnt vmcnt(14)
	ds_write_b128 v144, v[66:69] offset:16
	ds_write_b128 v144, v[70:73] offset:36880
	s_waitcnt lgkmcnt(6)
	v_mfma_f32_32x32x16_bf16 v[34:49], v[170:173], v[140:143], v[34:49]
	v_mfma_f32_32x32x16_bf16 v[18:33], v[162:165], v[154:157], v[18:33]
	s_waitcnt vmcnt(12)
	ds_write_b128 v144, v[74:77] offset:4624
	ds_write_b128 v144, v[78:81] offset:41488
	v_mfma_f32_32x32x16_bf16 v[2:17], v[170:173], v[154:157], v[2:17]
	s_waitcnt vmcnt(10)
	ds_write_b128 v144, v[82:85] offset:9232
	ds_write_b128 v144, v[86:89] offset:46096
	s_waitcnt lgkmcnt(7)
	v_mfma_f32_32x32x16_bf16 v[50:65], v[166:169], v[150:153], v[50:65]
	s_waitcnt vmcnt(8)
	ds_write_b128 v144, v[90:93] offset:13840
	ds_write_b128 v144, v[94:97] offset:50704
	s_waitcnt lgkmcnt(8)
	v_mfma_f32_32x32x16_bf16 v[34:49], v[174:177], v[150:153], v[34:49]
	v_mfma_f32_32x32x16_bf16 v[18:33], v[166:169], v[158:161], v[18:33]
	v_mfma_f32_32x32x16_bf16 v[2:17], v[174:177], v[158:161], v[2:17]
	s_add_i32 s20, s20, 2
	s_add_u32 s98, s98, 256
	s_addc_u32 s99, s99, 0
	s_add_u32 s100, s100, 256
	s_addc_u32 s101, s101, 0
	s_waitcnt lgkmcnt(0)
	s_barrier
; #define MFMA(a, b, c) __builtin_amdgcn_mfma_f32_32x32x16_bf16((a), (b), (c), 0, 0, 0)
; template <bool SWAP, class Epi>
; DI void gemm_tile(const u16* __restrict__ A, int lda, const u16* __restrict__ Bt, int ldb, int K, int m0, int n0, char* smem, Epi&& epi) {
;     ...
;   auto compute = [&](int buf) __attribute__((always_inline)) {
;     bf16x8 af[2][2], bfr[2][2];
;     af[0][0] = *(const bf16x8*)(Asb + buf * 128 * 72);
;     af[0][1] = *(const bf16x8*)(Asb + buf * 128 * 72 + 32 * 72);
;     bfr[0][0] = *(const bf16x8*)(Bsb + buf * 128 * 72);
;     bfr[0][1] = *(const bf16x8*)(Bsb + buf * 128 * 72 + 32 * 72);
; #pragma unroll
;     for (int ks = 0; ks < 4; ++ks) {
;       const int c = ks & 1, n = c ^ 1;
;       if (ks < 3) {
;         af[n][0] = *(const bf16x8*)(Asb + buf * 128 * 72 + (ks + 1) * 16);
;         af[n][1] = *(const bf16x8*)(Asb + buf * 128 * 72 + 32 * 72 + (ks + 1) * 16);
;         bfr[n][0] = *(const bf16x8*)(Bsb + buf * 128 * 72 + (ks + 1) * 16);
;         bfr[n][1] = *(const bf16x8*)(Bsb + buf * 128 * 72 + 32 * 72 + (ks + 1) * 16);
;       }
;       __builtin_amdgcn_sched_barrier(0);
; #pragma unroll
;       for (int mi = 0; mi < 2; ++mi)
; #pragma unroll
;         for (int ni = 0; ni < 2; ++ni) {
;           if (SWAP) acc[mi][ni] = MFMA(bfr[c][ni], af[c][mi], acc[mi][ni]);
;           else acc[mi][ni] = MFMA(af[c][mi], bfr[c][ni], acc[mi][ni]);
;         }
;       __builtin_amdgcn_sched_barrier(0);
;     }
;   };
;   for (int kt = 0; kt < KT; kt += 2) {
;     if (kt + 2 < KT) {
;       const int k0 = (kt + 2) << 6;
; #pragma unroll
;       for (int i = 0; i < 4; ++i) { ra0[i] = *(const u32x4*)(ag + (size_t)i * 32 * lda + k0); rb0[i] = *(const u32x4*)(bg + (size_t)i * 32 * ldb + k0); }
;     }
;     compute(0);
; #pragma unroll
;     for (int i = 0; i < 4; ++i) { *(u32x4*)(asw + 128 * 72 + 32 * i * 72) = ra1[i]; *(u32x4*)(bsw + 128 * 72 + 32 * i * 72) = rb1[i]; }
;     __syncthreads();
;     if (kt + 3 < KT) {
;       const int k0 = (kt + 3) << 6;
; #pragma unroll
;       for (int i = 0; i < 4; ++i) { ra1[i] = *(const u32x4*)(ag + (size_t)i * 32 * lda + k0); rb1[i] = *(const u32x4*)(bg + (size_t)i * 32 * ldb + k0); }
;     }
;     compute(1);
;     if (kt + 2 < KT) {
; #pragma unroll
;       for (int i = 0; i < 4; ++i) { *(u32x4*)(asw + 32 * i * 72) = ra0[i]; *(u32x4*)(bsw + 32 * i * 72) = rb0[i]; }
;     }
;     __syncthreads();
;   }
	s_cmp_lt_u32 s20, 30
	s_cbranch_scc1 .LBB0_748
	ds_read_b128 v[150:153], v147 offset:16
	ds_read_b128 v[154:157], v147 offset:48
	ds_read_b128 v[158:161], v147 offset:4624
	ds_read_b128 v[162:165], v147 offset:4656
	ds_read_b128 v[166:169], v148 offset:36880
	ds_read_b128 v[170:173], v148 offset:36912
	ds_read_b128 v[174:177], v148 offset:41488
	ds_read_b128 v[178:181], v148 offset:41520
	s_waitcnt lgkmcnt(3)
	v_mfma_f32_32x32x16_bf16 v[50:65], v[166:169], v[150:153], v[50:65]
	s_waitcnt lgkmcnt(1)
	v_mfma_f32_32x32x16_bf16 v[34:49], v[174:177], v[150:153], v[34:49]
	v_mfma_f32_32x32x16_bf16 v[18:33], v[166:169], v[158:161], v[18:33]
	v_mfma_f32_32x32x16_bf16 v[2:17], v[174:177], v[158:161], v[2:17]
	ds_read_b128 v[150:153], v147 offset:80
	ds_read_b128 v[158:161], v147 offset:4688
	ds_read_b128 v[166:169], v148 offset:36944
	ds_read_b128 v[174:177], v148 offset:41552
	v_mfma_f32_32x32x16_bf16 v[50:65], v[170:173], v[154:157], v[50:65]
	s_waitcnt lgkmcnt(4)
	v_mfma_f32_32x32x16_bf16 v[34:49], v[178:181], v[154:157], v[34:49]
	v_mfma_f32_32x32x16_bf16 v[18:33], v[170:173], v[162:165], v[18:33]
	v_mfma_f32_32x32x16_bf16 v[2:17], v[178:181], v[162:165], v[2:17]
	ds_read_b128 v[154:157], v147 offset:112
	ds_read_b128 v[162:165], v147 offset:4720
	ds_read_b128 v[170:173], v148 offset:36976
	ds_read_b128 v[178:181], v148 offset:41584
	s_waitcnt lgkmcnt(5)
	v_mfma_f32_32x32x16_bf16 v[50:65], v[166:169], v[150:153], v[50:65]
	s_waitcnt vmcnt(6)
	ds_write_b128 v144, v[98:101] offset:18448
	ds_write_b128 v144, v[102:105] offset:55312
	s_waitcnt lgkmcnt(6)
	v_mfma_f32_32x32x16_bf16 v[34:49], v[174:177], v[150:153], v[34:49]
	v_mfma_f32_32x32x16_bf16 v[18:33], v[166:169], v[158:161], v[18:33]
	s_waitcnt vmcnt(4)
	ds_write_b128 v144, v[106:109] offset:23056
	ds_write_b128 v144, v[110:113] offset:59920
	v_mfma_f32_32x32x16_bf16 v[2:17], v[174:177], v[158:161], v[2:17]
	s_waitcnt vmcnt(2)
	ds_write_b128 v144, v[114:117] offset:27664
	ds_write_b128 v144, v[118:121] offset:64528
	s_waitcnt lgkmcnt(7)
	v_mfma_f32_32x32x16_bf16 v[50:65], v[170:173], v[154:157], v[50:65]
	s_waitcnt vmcnt(0)
	ds_write_b128 v144, v[122:125] offset:32272
	ds_write_b128 v145, v[126:129] offset:32256
	s_waitcnt lgkmcnt(8)
	v_mfma_f32_32x32x16_bf16 v[34:49], v[178:181], v[154:157], v[34:49]
	v_mfma_f32_32x32x16_bf16 v[18:33], v[170:173], v[162:165], v[18:33]
	v_mfma_f32_32x32x16_bf16 v[2:17], v[178:181], v[162:165], v[2:17]
	s_waitcnt lgkmcnt(0)
	s_barrier
	ds_read_b128 v[140:143], v147 offset:18448
	ds_read_b128 v[150:153], v147 offset:18480
	ds_read_b128 v[154:157], v147 offset:23056
	ds_read_b128 v[158:161], v147 offset:23088
	ds_read_b128 v[162:165], v148 offset:55312
	ds_read_b128 v[166:169], v148 offset:55344
	ds_read_b128 v[170:173], v148 offset:59920
	ds_read_b128 v[174:177], v148 offset:59952
	s_waitcnt lgkmcnt(3)
	v_mfma_f32_32x32x16_bf16 v[50:65], v[162:165], v[140:143], v[50:65]
	s_waitcnt lgkmcnt(1)
	v_mfma_f32_32x32x16_bf16 v[34:49], v[170:173], v[140:143], v[34:49]
	v_mfma_f32_32x32x16_bf16 v[18:33], v[162:165], v[154:157], v[18:33]
	v_mfma_f32_32x32x16_bf16 v[2:17], v[170:173], v[154:157], v[2:17]
	ds_read_b128 v[140:143], v147 offset:18512
	ds_read_b128 v[154:157], v147 offset:23120
	ds_read_b128 v[162:165], v148 offset:55376
	ds_read_b128 v[170:173], v148 offset:59984
	v_mfma_f32_32x32x16_bf16 v[50:65], v[166:169], v[150:153], v[50:65]
	s_waitcnt lgkmcnt(4)
	v_mfma_f32_32x32x16_bf16 v[34:49], v[174:177], v[150:153], v[34:49]
	v_mfma_f32_32x32x16_bf16 v[18:33], v[166:169], v[158:161], v[18:33]
	v_mfma_f32_32x32x16_bf16 v[2:17], v[174:177], v[158:161], v[2:17]
	ds_read_b128 v[150:153], v147 offset:18544
	ds_read_b128 v[158:161], v147 offset:23152
	ds_read_b128 v[166:169], v148 offset:55408
	ds_read_b128 v[174:177], v148 offset:60016
	s_waitcnt lgkmcnt(5)
	v_mfma_f32_32x32x16_bf16 v[50:65], v[162:165], v[140:143], v[50:65]
	s_waitcnt lgkmcnt(4)
	v_mfma_f32_32x32x16_bf16 v[34:49], v[170:173], v[140:143], v[34:49]
	v_mfma_f32_32x32x16_bf16 v[18:33], v[162:165], v[154:157], v[18:33]
	v_mfma_f32_32x32x16_bf16 v[2:17], v[170:173], v[154:157], v[2:17]
	s_waitcnt lgkmcnt(1)
	v_mfma_f32_32x32x16_bf16 v[50:65], v[166:169], v[150:153], v[50:65]
	s_waitcnt lgkmcnt(0)
	v_mfma_f32_32x32x16_bf16 v[34:49], v[174:177], v[150:153], v[34:49]
	v_mfma_f32_32x32x16_bf16 v[18:33], v[166:169], v[158:161], v[18:33]
	v_mfma_f32_32x32x16_bf16 v[2:17], v[174:177], v[158:161], v[2:17]
	s_waitcnt lgkmcnt(0)
	s_barrier
	s_branch .LBB0_745

; template <bool SWAP, class Epi>
; DI void gemm_tile(const u16* __restrict__ A, int lda, const u16* __restrict__ Bt, int ldb, int K, int m0, int n0, char* smem, Epi&& epi) {
;   u16* As = (u16*)(smem + 16);
;   u16* Bs = As + 2 * 128 * 72;
;   const int tid = threadIdx.x, lane = tid & 63, w = tid >> 6, wm = w >> 1, wn = w & 1;
;   const int r = lane & 31, hi = lane >> 5;
;   f32x16 acc[2][2];
; #pragma unroll
;   for (int a = 0; a < 2; ++a)
; #pragma unroll
;     for (int b = 0; b < 2; ++b)
; #pragma unroll
;       for (int i = 0; i < 16; ++i) acc[a][b][i] = 0.f;
;   const int srow = tid >> 3, skc = tid & 7;
;   const u16* ag = A + (size_t)(m0 + srow) * lda + skc * 8;
;   const u16* bg = Bt + (size_t)(n0 + srow) * ldb + skc * 8;
;   u16* asw = As + srow * 72 + skc * 8;
;   u16* bsw = Bs + srow * 72 + skc * 8;
;   u32x4 ra0[4], rb0[4], ra1[4], rb1[4];
; #pragma unroll
;   for (int i = 0; i < 4; ++i) { ra0[i] = *(const u32x4*)(ag + (size_t)i * 32 * lda); rb0[i] = *(const u32x4*)(bg + (size_t)i * 32 * ldb); }
; #pragma unroll
;   for (int i = 0; i < 4; ++i) { ra1[i] = *(const u32x4*)(ag + (size_t)i * 32 * lda + 64); rb1[i] = *(const u32x4*)(bg + (size_t)i * 32 * ldb + 64); }
;   __syncthreads();
; #pragma unroll
;   for (int i = 0; i < 4; ++i) { *(u32x4*)(asw + 32 * i * 72) = ra0[i]; *(u32x4*)(bsw + 32 * i * 72) = rb0[i]; }
;   __syncthreads();
;   const int KT = K >> 6;
;   const u16* Asb = As + (wm * 64 + r) * 72 + hi * 8;
;   const u16* Bsb = Bs + (wn * 64 + r) * 72 + hi * 8;
.LBB0_953:
	s_ashr_i32 s6, s15, 31
	s_lshr_b32 s6, s6, 26
	s_add_i32 s6, s15, s6
	s_and_b32 s7, s6, 0x1ffffc0
	s_sub_i32 s7, s15, s7
	s_lshl_b32 s16, s7, 7
	s_lshl_b32 s6, s6, 1
	v_or_b32_e32 v2, s16, v1
	s_and_b32 s17, s6, 0xffffff80
	v_ashrrev_i32_e32 v3, 31, v2
	v_lshlrev_b64 v[22:23], 12, v[2:3]
	v_or_b32_e32 v2, s17, v1
	v_lshl_add_u64 v[4:5], v[132:133], 0, v[22:23]
	v_ashrrev_i32_e32 v3, 31, v2
	v_lshlrev_b64 v[24:25], 12, v[2:3]
	v_add_co_u32_e32 v8, vcc, s11, v4
	v_lshl_add_u64 v[6:7], v[134:135], 0, v[24:25]
	s_nop 0
	v_addc_co_u32_e32 v9, vcc, 0, v5, vcc
	v_add_co_u32_e32 v10, vcc, s11, v6
	global_load_dwordx4 v[66:69], v[4:5], off
	global_load_dwordx4 v[70:73], v[6:7], off
	v_addc_co_u32_e32 v11, vcc, 0, v7, vcc
	v_add_co_u32_e32 v12, vcc, s13, v4
	global_load_dwordx4 v[74:77], v[8:9], off
	global_load_dwordx4 v[78:81], v[10:11], off
	v_addc_co_u32_e32 v13, vcc, 0, v5, vcc
	v_add_co_u32_e32 v14, vcc, s13, v6
	global_load_dwordx4 v[82:85], v[12:13], off
	s_nop 0
	v_addc_co_u32_e32 v15, vcc, 0, v7, vcc
	v_add_co_u32_e32 v16, vcc, s14, v6
	global_load_dwordx4 v[86:89], v[14:15], off
	s_nop 0
	v_addc_co_u32_e32 v17, vcc, 0, v7, vcc
	v_add_co_u32_e32 v18, vcc, s14, v4
	global_load_dwordx4 v[94:97], v[16:17], off
	s_nop 0
	v_addc_co_u32_e32 v19, vcc, 0, v5, vcc
	global_load_dwordx4 v[90:93], v[18:19], off
	global_load_dwordx4 v[98:101], v[4:5], off offset:128
	global_load_dwordx4 v[102:105], v[6:7], off offset:128
	global_load_dwordx4 v[106:109], v[8:9], off offset:128
	global_load_dwordx4 v[110:113], v[10:11], off offset:128
	global_load_dwordx4 v[114:117], v[12:13], off offset:128
	global_load_dwordx4 v[118:121], v[14:15], off offset:128
	global_load_dwordx4 v[122:125], v[18:19], off offset:128
	global_load_dwordx4 v[126:129], v[16:17], off offset:128
	s_mov_b32 s18, 0
	v_mov_b32_e32 v2, 0
	v_mov_b32_e32 v3, v131
	v_mov_b32_e32 v4, v131
	v_mov_b32_e32 v5, v131
	v_mov_b32_e32 v6, v131
	v_mov_b32_e32 v7, v131
	v_mov_b32_e32 v8, v131
	v_mov_b32_e32 v9, v131
	v_mov_b32_e32 v10, v131
	v_mov_b32_e32 v11, v131
	v_mov_b32_e32 v12, v131
	v_mov_b32_e32 v13, v131
	v_mov_b32_e32 v14, v131
	v_mov_b32_e32 v15, v131
	v_mov_b32_e32 v16, v131
	v_mov_b32_e32 v17, v131
	v_mov_b32_e32 v18, 0
	v_mov_b32_e32 v19, v131
	v_mov_b32_e32 v20, v131
	v_lshl_add_u64 v[136:137], s[82:83], 0, v[24:25]
	v_lshl_add_u64 v[138:139], s[82:83], 0, v[22:23]
	v_add_u32_e32 v190, v24, v130
	v_add_u32_e32 v191, 0x20000, v190
	v_add_u32_e32 v192, 0x40000, v190
	v_add_u32_e32 v193, 0x60000, v190
	s_add_u32 s98, s82, 0x1cb8000
	s_addc_u32 s99, s83, 0
	v_add_u32_e32 v194, v22, v130
	v_add_u32_e32 v195, 0x20000, v194
	v_add_u32_e32 v196, 0x40000, v194
	v_add_u32_e32 v197, 0x60000, v194
	s_add_u32 s100, s82, 0x6538000
	s_addc_u32 s101, s83, 0
	v_mov_b32_e32 v21, v131
	v_mov_b32_e32 v22, v131
	v_mov_b32_e32 v23, v131
	v_mov_b32_e32 v24, v131
	v_mov_b32_e32 v25, v131
	v_mov_b32_e32 v26, v131
	v_mov_b32_e32 v27, v131
	v_mov_b32_e32 v28, v131
	v_mov_b32_e32 v29, v131
	v_mov_b32_e32 v30, v131
	v_mov_b32_e32 v31, v131
	v_mov_b32_e32 v32, v131
	v_mov_b32_e32 v33, v131
	v_mov_b32_e32 v34, 0
	v_mov_b32_e32 v35, v131
	v_mov_b32_e32 v36, v131
	v_mov_b32_e32 v37, v131
	v_mov_b32_e32 v38, v131
	v_mov_b32_e32 v39, v131
	v_mov_b32_e32 v40, v131
	v_mov_b32_e32 v41, v131
	v_mov_b32_e32 v42, v131
	v_mov_b32_e32 v43, v131
	v_mov_b32_e32 v44, v131
	v_mov_b32_e32 v45, v131
	v_mov_b32_e32 v46, v131
	v_mov_b32_e32 v47, v131
	v_mov_b32_e32 v48, v131
	v_mov_b32_e32 v49, v131
	v_mov_b32_e32 v50, 0
	v_mov_b32_e32 v51, v131
	v_mov_b32_e32 v52, v131
	v_mov_b32_e32 v53, v131
	v_mov_b32_e32 v54, v131
	v_mov_b32_e32 v55, v131
	v_mov_b32_e32 v56, v131
	v_mov_b32_e32 v57, v131
	v_mov_b32_e32 v58, v131
	v_mov_b32_e32 v59, v131
	v_mov_b32_e32 v60, v131
	v_mov_b32_e32 v61, v131
	v_mov_b32_e32 v62, v131
	v_mov_b32_e32 v63, v131
	v_mov_b32_e32 v64, v131
	v_mov_b32_e32 v65, v131
	s_waitcnt lgkmcnt(0)
	s_barrier
	s_waitcnt vmcnt(14)
	ds_write_b128 v144, v[70:73] offset:36880
	ds_write_b128 v144, v[66:69] offset:16
	s_waitcnt vmcnt(12)
	ds_write_b128 v144, v[78:81] offset:41488
	s_waitcnt vmcnt(10)
	ds_write_b128 v144, v[86:89] offset:46096
	s_waitcnt vmcnt(9)
	ds_write_b128 v144, v[94:97] offset:50704
	ds_write_b128 v144, v[74:77] offset:4624
	ds_write_b128 v144, v[82:85] offset:9232
	s_waitcnt vmcnt(8)
	ds_write_b128 v144, v[90:93] offset:13840
	s_waitcnt lgkmcnt(0)
	s_barrier
	s_branch .LBB0_955
; #define MFMA(a, b, c) __builtin_amdgcn_mfma_f32_32x32x16_bf16((a), (b), (c), 0, 0, 0)
; template <bool SWAP, class Epi>
; DI void gemm_tile(const u16* __restrict__ A, int lda, const u16* __restrict__ Bt, int ldb, int K, int m0, int n0, char* smem, Epi&& epi) {
;     ...
;   auto compute = [&](int buf) __attribute__((always_inline)) {
;     bf16x8 af[2][2], bfr[2][2];
;     af[0][0] = *(const bf16x8*)(Asb + buf * 128 * 72);
;     af[0][1] = *(const bf16x8*)(Asb + buf * 128 * 72 + 32 * 72);
;     bfr[0][0] = *(const bf16x8*)(Bsb + buf * 128 * 72);
;     bfr[0][1] = *(const bf16x8*)(Bsb + buf * 128 * 72 + 32 * 72);
; #pragma unroll
;     for (int ks = 0; ks < 4; ++ks) {
;       const int c = ks & 1, n = c ^ 1;
;       if (ks < 3) {
;         af[n][0] = *(const bf16x8*)(Asb + buf * 128 * 72 + (ks + 1) * 16);
;         af[n][1] = *(const bf16x8*)(Asb + buf * 128 * 72 + 32 * 72 + (ks + 1) * 16);
;         bfr[n][0] = *(const bf16x8*)(Bsb + buf * 128 * 72 + (ks + 1) * 16);
;         bfr[n][1] = *(const bf16x8*)(Bsb + buf * 128 * 72 + 32 * 72 + (ks + 1) * 16);
;       }
;       __builtin_amdgcn_sched_barrier(0);
; #pragma unroll
;       for (int mi = 0; mi < 2; ++mi)
; #pragma unroll
;         for (int ni = 0; ni < 2; ++ni) {
;           if (SWAP) acc[mi][ni] = MFMA(bfr[c][ni], af[c][mi], acc[mi][ni]);
;           else acc[mi][ni] = MFMA(af[c][mi], bfr[c][ni], acc[mi][ni]);
;         }
;       __builtin_amdgcn_sched_barrier(0);
;     }
;   };
;   for (int kt = 0; kt < KT; kt += 2) {
;     if (kt + 2 < KT) {
;       const int k0 = (kt + 2) << 6;
; #pragma unroll
;       for (int i = 0; i < 4; ++i) { ra0[i] = *(const u32x4*)(ag + (size_t)i * 32 * lda + k0); rb0[i] = *(const u32x4*)(bg + (size_t)i * 32 * ldb + k0); }
;     }
;     compute(0);
; #pragma unroll
;     for (int i = 0; i < 4; ++i) { *(u32x4*)(asw + 128 * 72 + 32 * i * 72) = ra1[i]; *(u32x4*)(bsw + 128 * 72 + 32 * i * 72) = rb1[i]; }
;     __syncthreads();
;     if (kt + 3 < KT) {
;       const int k0 = (kt + 3) << 6;
; #pragma unroll
;       for (int i = 0; i < 4; ++i) { ra1[i] = *(const u32x4*)(ag + (size_t)i * 32 * lda + k0); rb1[i] = *(const u32x4*)(bg + (size_t)i * 32 * ldb + k0); }
;     }
;     compute(1);
;     if (kt + 2 < KT) {
; #pragma unroll
;       for (int i = 0; i < 4; ++i) { *(u32x4*)(asw + 32 * i * 72) = ra0[i]; *(u32x4*)(bsw + 32 * i * 72) = rb0[i]; }
;     }
;     __syncthreads();
;   }
.LBB0_955:
	global_load_dwordx4 v[66:69], v194, s[100:101] offset:256
	global_load_dwordx4 v[70:73], v190, s[98:99] offset:256
	global_load_dwordx4 v[74:77], v195, s[100:101] offset:256
	global_load_dwordx4 v[78:81], v191, s[98:99] offset:256
	global_load_dwordx4 v[82:85], v196, s[100:101] offset:256
	global_load_dwordx4 v[86:89], v192, s[98:99] offset:256
	global_load_dwordx4 v[90:93], v197, s[100:101] offset:256
	global_load_dwordx4 v[94:97], v193, s[98:99] offset:256
	ds_read_b128 v[150:153], v147 offset:16
	ds_read_b128 v[154:157], v147 offset:48
	ds_read_b128 v[158:161], v147 offset:4624
	ds_read_b128 v[162:165], v147 offset:4656
	ds_read_b128 v[166:169], v148 offset:36880
	ds_read_b128 v[170:173], v148 offset:36912
	ds_read_b128 v[174:177], v148 offset:41488
	ds_read_b128 v[178:181], v148 offset:41520
	s_waitcnt lgkmcnt(3)
	v_mfma_f32_32x32x16_bf16 v[50:65], v[166:169], v[150:153], v[50:65]
	s_waitcnt lgkmcnt(1)
	v_mfma_f32_32x32x16_bf16 v[34:49], v[174:177], v[150:153], v[34:49]
	v_mfma_f32_32x32x16_bf16 v[18:33], v[166:169], v[158:161], v[18:33]
	v_mfma_f32_32x32x16_bf16 v[2:17], v[174:177], v[158:161], v[2:17]
	ds_read_b128 v[150:153], v147 offset:80
	ds_read_b128 v[158:161], v147 offset:4688
	ds_read_b128 v[166:169], v148 offset:36944
	ds_read_b128 v[174:177], v148 offset:41552
	v_mfma_f32_32x32x16_bf16 v[50:65], v[170:173], v[154:157], v[50:65]
	s_waitcnt lgkmcnt(4)
	v_mfma_f32_32x32x16_bf16 v[34:49], v[178:181], v[154:157], v[34:49]
	v_mfma_f32_32x32x16_bf16 v[18:33], v[170:173], v[162:165], v[18:33]
	v_mfma_f32_32x32x16_bf16 v[2:17], v[178:181], v[162:165], v[2:17]
	ds_read_b128 v[154:157], v147 offset:112
	ds_read_b128 v[162:165], v147 offset:4720
	ds_read_b128 v[170:173], v148 offset:36976
	ds_read_b128 v[178:181], v148 offset:41584
	s_waitcnt lgkmcnt(5)
	v_mfma_f32_32x32x16_bf16 v[50:65], v[166:169], v[150:153], v[50:65]
	s_waitcnt vmcnt(14)
	ds_write_b128 v144, v[98:101] offset:18448
	ds_write_b128 v144, v[102:105] offset:55312
	s_waitcnt lgkmcnt(6)
	v_mfma_f32_32x32x16_bf16 v[34:49], v[174:177], v[150:153], v[34:49]
	v_mfma_f32_32x32x16_bf16 v[18:33], v[166:169], v[158:161], v[18:33]
	s_waitcnt vmcnt(12)
	ds_write_b128 v144, v[106:109] offset:23056
	ds_write_b128 v144, v[110:113] offset:59920
	v_mfma_f32_32x32x16_bf16 v[2:17], v[174:177], v[158:161], v[2:17]
	s_waitcnt vmcnt(10)
	ds_write_b128 v144, v[114:117] offset:27664
	ds_write_b128 v144, v[118:121] offset:64528
	s_waitcnt lgkmcnt(7)
	v_mfma_f32_32x32x16_bf16 v[50:65], v[170:173], v[154:157], v[50:65]
	s_waitcnt vmcnt(8)
	ds_write_b128 v144, v[122:125] offset:32272
	ds_write_b128 v145, v[126:129] offset:32256
	s_waitcnt lgkmcnt(8)
	v_mfma_f32_32x32x16_bf16 v[34:49], v[178:181], v[154:157], v[34:49]
	v_mfma_f32_32x32x16_bf16 v[18:33], v[170:173], v[162:165], v[18:33]
	v_mfma_f32_32x32x16_bf16 v[2:17], v[178:181], v[162:165], v[2:17]
	s_waitcnt lgkmcnt(0)
	s_barrier
	global_load_dwordx4 v[98:101], v194, s[100:101] offset:384
	global_load_dwordx4 v[102:105], v190, s[98:99] offset:384
	global_load_dwordx4 v[106:109], v195, s[100:101] offset:384
	global_load_dwordx4 v[110:113], v191, s[98:99] offset:384
	global_load_dwordx4 v[114:117], v196, s[100:101] offset:384
	global_load_dwordx4 v[118:121], v192, s[98:99] offset:384
	global_load_dwordx4 v[122:125], v197, s[100:101] offset:384
	global_load_dwordx4 v[126:129], v193, s[98:99] offset:384
	ds_read_b128 v[140:143], v147 offset:18448
	ds_read_b128 v[150:153], v147 offset:18480
	ds_read_b128 v[154:157], v147 offset:23056
	ds_read_b128 v[158:161], v147 offset:23088
	ds_read_b128 v[162:165], v148 offset:55312
	ds_read_b128 v[166:169], v148 offset:55344
	ds_read_b128 v[170:173], v148 offset:59920
	ds_read_b128 v[174:177], v148 offset:59952
	s_waitcnt lgkmcnt(3)
	v_mfma_f32_32x32x16_bf16 v[50:65], v[162:165], v[140:143], v[50:65]
	s_waitcnt lgkmcnt(1)
	v_mfma_f32_32x32x16_bf16 v[34:49], v[170:173], v[140:143], v[34:49]
	v_mfma_f32_32x32x16_bf16 v[18:33], v[162:165], v[154:157], v[18:33]
	v_mfma_f32_32x32x16_bf16 v[2:17], v[170:173], v[154:157], v[2:17]
	ds_read_b128 v[140:143], v147 offset:18512
	ds_read_b128 v[154:157], v147 offset:23120
	ds_read_b128 v[162:165], v148 offset:55376
	ds_read_b128 v[170:173], v148 offset:59984
	v_mfma_f32_32x32x16_bf16 v[50:65], v[166:169], v[150:153], v[50:65]
	s_waitcnt lgkmcnt(4)
	v_mfma_f32_32x32x16_bf16 v[34:49], v[174:177], v[150:153], v[34:49]
	v_mfma_f32_32x32x16_bf16 v[18:33], v[166:169], v[158:161], v[18:33]
	v_mfma_f32_32x32x16_bf16 v[2:17], v[174:177], v[158:161], v[2:17]
	ds_read_b128 v[150:153], v147 offset:18544
	ds_read_b128 v[158:161], v147 offset:23152
	ds_read_b128 v[166:169], v148 offset:55408
	ds_read_b128 v[174:177], v148 offset:60016
	s_waitcnt lgkmcnt(5)
	v_mfma_f32_32x32x16_bf16 v[50:65], v[162:165], v[140:143], v[50:65]
	s_waitcnt vmcnt(14)
	ds_write_b128 v144, v[66:69] offset:16
	ds_write_b128 v144, v[70:73] offset:36880
	s_waitcnt lgkmcnt(6)
	v_mfma_f32_32x32x16_bf16 v[34:49], v[170:173], v[140:143], v[34:49]
	v_mfma_f32_32x32x16_bf16 v[18:33], v[162:165], v[154:157], v[18:33]
	s_waitcnt vmcnt(12)
	ds_write_b128 v144, v[74:77] offset:4624
	ds_write_b128 v144, v[78:81] offset:41488
	v_mfma_f32_32x32x16_bf16 v[2:17], v[170:173], v[154:157], v[2:17]
	s_waitcnt vmcnt(10)
	ds_write_b128 v144, v[82:85] offset:9232
	ds_write_b128 v144, v[86:89] offset:46096
	s_waitcnt lgkmcnt(7)
	v_mfma_f32_32x32x16_bf16 v[50:65], v[166:169], v[150:153], v[50:65]
	s_waitcnt vmcnt(8)
	ds_write_b128 v144, v[90:93] offset:13840
	ds_write_b128 v144, v[94:97] offset:50704
	s_waitcnt lgkmcnt(8)
	v_mfma_f32_32x32x16_bf16 v[34:49], v[174:177], v[150:153], v[34:49]
	v_mfma_f32_32x32x16_bf16 v[18:33], v[166:169], v[158:161], v[18:33]
	v_mfma_f32_32x32x16_bf16 v[2:17], v[174:177], v[158:161], v[2:17]
	s_add_i32 s18, s18, 2
	s_add_u32 s98, s98, 256
	s_addc_u32 s99, s99, 0
	s_add_u32 s100, s100, 256
	s_addc_u32 s101, s101, 0
	s_waitcnt lgkmcnt(0)
	s_barrier
; #define MFMA(a, b, c) __builtin_amdgcn_mfma_f32_32x32x16_bf16((a), (b), (c), 0, 0, 0)
; template <bool SWAP, class Epi>
; DI void gemm_tile(const u16* __restrict__ A, int lda, const u16* __restrict__ Bt, int ldb, int K, int m0, int n0, char* smem, Epi&& epi) {
;     ...
;   auto compute = [&](int buf) __attribute__((always_inline)) {
;     bf16x8 af[2][2], bfr[2][2];
;     af[0][0] = *(const bf16x8*)(Asb + buf * 128 * 72);
;     af[0][1] = *(const bf16x8*)(Asb + buf * 128 * 72 + 32 * 72);
;     bfr[0][0] = *(const bf16x8*)(Bsb + buf * 128 * 72);
;     bfr[0][1] = *(const bf16x8*)(Bsb + buf * 128 * 72 + 32 * 72);
; #pragma unroll
;     for (int ks = 0; ks < 4; ++ks) {
;       const int c = ks & 1, n = c ^ 1;
;       if (ks < 3) {
;         af[n][0] = *(const bf16x8*)(Asb + buf * 128 * 72 + (ks + 1) * 16);
;         af[n][1] = *(const bf16x8*)(Asb + buf * 128 * 72 + 32 * 72 + (ks + 1) * 16);
;         bfr[n][0] = *(const bf16x8*)(Bsb + buf * 128 * 72 + (ks + 1) * 16);
;         bfr[n][1] = *(const bf16x8*)(Bsb + buf * 128 * 72 + 32 * 72 + (ks + 1) * 16);
;       }
;       __builtin_amdgcn_sched_barrier(0);
; #pragma unroll
;       for (int mi = 0; mi < 2; ++mi)
; #pragma unroll
;         for (int ni = 0; ni < 2; ++ni) {
;           if (SWAP) acc[mi][ni] = MFMA(bfr[c][ni], af[c][mi], acc[mi][ni]);
;           else acc[mi][ni] = MFMA(af[c][mi], bfr[c][ni], acc[mi][ni]);
;         }
;       __builtin_amdgcn_sched_barrier(0);
;     }
;   };
;   for (int kt = 0; kt < KT; kt += 2) {
;     if (kt + 2 < KT) {
;       const int k0 = (kt + 2) << 6;
; #pragma unroll
;       for (int i = 0; i < 4; ++i) { ra0[i] = *(const u32x4*)(ag + (size_t)i * 32 * lda + k0); rb0[i] = *(const u32x4*)(bg + (size_t)i * 32 * ldb + k0); }
;     }
;     compute(0);
; #pragma unroll
;     for (int i = 0; i < 4; ++i) { *(u32x4*)(asw + 128 * 72 + 32 * i * 72) = ra1[i]; *(u32x4*)(bsw + 128 * 72 + 32 * i * 72) = rb1[i]; }
;     __syncthreads();
;     if (kt + 3 < KT) {
;       const int k0 = (kt + 3) << 6;
; #pragma unroll
;       for (int i = 0; i < 4; ++i) { ra1[i] = *(const u32x4*)(ag + (size_t)i * 32 * lda + k0); rb1[i] = *(const u32x4*)(bg + (size_t)i * 32 * ldb + k0); }
;     }
;     compute(1);
;     if (kt + 2 < KT) {
; #pragma unroll
;       for (int i = 0; i < 4; ++i) { *(u32x4*)(asw + 32 * i * 72) = ra0[i]; *(u32x4*)(bsw + 32 * i * 72) = rb0[i]; }
;     }
;     __syncthreads();
;   }
	s_cmp_lt_u32 s18, 30
	s_cbranch_scc1 .LBB0_955
	ds_read_b128 v[150:153], v147 offset:16
	ds_read_b128 v[154:157], v147 offset:48
	ds_read_b128 v[158:161], v147 offset:4624
	ds_read_b128 v[162:165], v147 offset:4656
	ds_read_b128 v[166:169], v148 offset:36880
	ds_read_b128 v[170:173], v148 offset:36912
	ds_read_b128 v[174:177], v148 offset:41488
	ds_read_b128 v[178:181], v148 offset:41520
	s_waitcnt lgkmcnt(3)
	v_mfma_f32_32x32x16_bf16 v[50:65], v[166:169], v[150:153], v[50:65]
	s_waitcnt lgkmcnt(1)
	v_mfma_f32_32x32x16_bf16 v[34:49], v[174:177], v[150:153], v[34:49]
	v_mfma_f32_32x32x16_bf16 v[18:33], v[166:169], v[158:161], v[18:33]
	v_mfma_f32_32x32x16_bf16 v[2:17], v[174:177], v[158:161], v[2:17]
	ds_read_b128 v[150:153], v147 offset:80
	ds_read_b128 v[158:161], v147 offset:4688
	ds_read_b128 v[166:169], v148 offset:36944
	ds_read_b128 v[174:177], v148 offset:41552
	v_mfma_f32_32x32x16_bf16 v[50:65], v[170:173], v[154:157], v[50:65]
	s_waitcnt lgkmcnt(4)
	v_mfma_f32_32x32x16_bf16 v[34:49], v[178:181], v[154:157], v[34:49]
	v_mfma_f32_32x32x16_bf16 v[18:33], v[170:173], v[162:165], v[18:33]
	v_mfma_f32_32x32x16_bf16 v[2:17], v[178:181], v[162:165], v[2:17]
	ds_read_b128 v[154:157], v147 offset:112
	ds_read_b128 v[162:165], v147 offset:4720
	ds_read_b128 v[170:173], v148 offset:36976
	ds_read_b128 v[178:181], v148 offset:41584
	s_waitcnt lgkmcnt(5)
	v_mfma_f32_32x32x16_bf16 v[50:65], v[166:169], v[150:153], v[50:65]
	s_waitcnt vmcnt(6)
	ds_write_b128 v144, v[98:101] offset:18448
	ds_write_b128 v144, v[102:105] offset:55312
	s_waitcnt lgkmcnt(6)
	v_mfma_f32_32x32x16_bf16 v[34:49], v[174:177], v[150:153], v[34:49]
	v_mfma_f32_32x32x16_bf16 v[18:33], v[166:169], v[158:161], v[18:33]
	s_waitcnt vmcnt(4)
	ds_write_b128 v144, v[106:109] offset:23056
	ds_write_b128 v144, v[110:113] offset:59920
	v_mfma_f32_32x32x16_bf16 v[2:17], v[174:177], v[158:161], v[2:17]
	s_waitcnt vmcnt(2)
	ds_write_b128 v144, v[114:117] offset:27664
	ds_write_b128 v144, v[118:121] offset:64528
	s_waitcnt lgkmcnt(7)
	v_mfma_f32_32x32x16_bf16 v[50:65], v[170:173], v[154:157], v[50:65]
	s_waitcnt vmcnt(0)
	ds_write_b128 v144, v[122:125] offset:32272
	ds_write_b128 v145, v[126:129] offset:32256
	s_waitcnt lgkmcnt(8)
	v_mfma_f32_32x32x16_bf16 v[34:49], v[178:181], v[154:157], v[34:49]
	v_mfma_f32_32x32x16_bf16 v[18:33], v[170:173], v[162:165], v[18:33]
	v_mfma_f32_32x32x16_bf16 v[2:17], v[178:181], v[162:165], v[2:17]
	s_waitcnt lgkmcnt(0)
	s_barrier
	ds_read_b128 v[140:143], v147 offset:18448
	ds_read_b128 v[150:153], v147 offset:18480
	ds_read_b128 v[154:157], v147 offset:23056
	ds_read_b128 v[158:161], v147 offset:23088
	ds_read_b128 v[162:165], v148 offset:55312
	ds_read_b128 v[166:169], v148 offset:55344
	ds_read_b128 v[170:173], v148 offset:59920
	ds_read_b128 v[174:177], v148 offset:59952
	s_waitcnt lgkmcnt(3)
	v_mfma_f32_32x32x16_bf16 v[50:65], v[162:165], v[140:143], v[50:65]
	s_waitcnt lgkmcnt(1)
	v_mfma_f32_32x32x16_bf16 v[34:49], v[170:173], v[140:143], v[34:49]
	v_mfma_f32_32x32x16_bf16 v[18:33], v[162:165], v[154:157], v[18:33]
	v_mfma_f32_32x32x16_bf16 v[2:17], v[170:173], v[154:157], v[2:17]
	ds_read_b128 v[140:143], v147 offset:18512
	ds_read_b128 v[154:157], v147 offset:23120
	ds_read_b128 v[162:165], v148 offset:55376
	ds_read_b128 v[170:173], v148 offset:59984
	v_mfma_f32_32x32x16_bf16 v[50:65], v[166:169], v[150:153], v[50:65]
	s_waitcnt lgkmcnt(4)
	v_mfma_f32_32x32x16_bf16 v[34:49], v[174:177], v[150:153], v[34:49]
	v_mfma_f32_32x32x16_bf16 v[18:33], v[166:169], v[158:161], v[18:33]
	v_mfma_f32_32x32x16_bf16 v[2:17], v[174:177], v[158:161], v[2:17]
	ds_read_b128 v[150:153], v147 offset:18544
	ds_read_b128 v[158:161], v147 offset:23152
	ds_read_b128 v[166:169], v148 offset:55408
	ds_read_b128 v[174:177], v148 offset:60016
	s_waitcnt lgkmcnt(5)
	v_mfma_f32_32x32x16_bf16 v[50:65], v[162:165], v[140:143], v[50:65]
	s_waitcnt lgkmcnt(4)
	v_mfma_f32_32x32x16_bf16 v[34:49], v[170:173], v[140:143], v[34:49]
	v_mfma_f32_32x32x16_bf16 v[18:33], v[162:165], v[154:157], v[18:33]
	v_mfma_f32_32x32x16_bf16 v[2:17], v[170:173], v[154:157], v[2:17]
	s_waitcnt lgkmcnt(1)
	v_mfma_f32_32x32x16_bf16 v[50:65], v[166:169], v[150:153], v[50:65]
	s_waitcnt lgkmcnt(0)
	v_mfma_f32_32x32x16_bf16 v[34:49], v[174:177], v[150:153], v[34:49]
	v_mfma_f32_32x32x16_bf16 v[18:33], v[166:169], v[158:161], v[18:33]
	v_mfma_f32_32x32x16_bf16 v[2:17], v[174:177], v[158:161], v[2:17]
	s_waitcnt lgkmcnt(0)
	s_barrier
	s_branch .LBB0_952

; __global__ void __launch_bounds__(256, 2) mega(Params p) {
;   extern __shared__ __attribute__((aligned(16))) char smem[];
	.amdhsa_kernel _Z4mega6Params
		.amdhsa_group_segment_fixed_size 0
		.amdhsa_private_segment_fixed_size 0
		.amdhsa_kernarg_size 448
		.amdhsa_user_sgpr_count 2
		.amdhsa_user_sgpr_dispatch_ptr 0
		.amdhsa_user_sgpr_queue_ptr 0
		.amdhsa_user_sgpr_kernarg_segment_ptr 1
		.amdhsa_user_sgpr_dispatch_id 0
		.amdhsa_user_sgpr_kernarg_preload_length 0
		.amdhsa_user_sgpr_kernarg_preload_offset 0
		.amdhsa_user_sgpr_private_segment_size 0
		.amdhsa_uses_dynamic_stack 0
		.amdhsa_enable_private_segment 0
		.amdhsa_system_sgpr_workgroup_id_x 1
		.amdhsa_system_sgpr_workgroup_id_y 0
		.amdhsa_system_sgpr_workgroup_id_z 0
		.amdhsa_system_sgpr_workgroup_info 0
		.amdhsa_system_vgpr_workitem_id 0
		.amdhsa_next_free_vgpr 246
		.amdhsa_next_free_sgpr 102
		.amdhsa_accum_offset 248
		.amdhsa_reserve_vcc 1
		.amdhsa_float_round_mode_32 0
		.amdhsa_float_round_mode_16_64 0
		.amdhsa_float_denorm_mode_32 3
		.amdhsa_float_denorm_mode_16_64 3
		.amdhsa_dx10_clamp 1
		.amdhsa_ieee_mode 1
		.amdhsa_fp16_overflow 0
		.amdhsa_tg_split 0
		.amdhsa_exception_fp_ieee_invalid_op 0
		.amdhsa_exception_fp_denorm_src 0
		.amdhsa_exception_fp_ieee_div_zero 0
		.amdhsa_exception_fp_ieee_overflow 0
		.amdhsa_exception_fp_ieee_underflow 0
		.amdhsa_exception_fp_ieee_inexact 0
		.amdhsa_exception_int_div_zero 0
	.end_amdhsa_kernel

; __global__ void __launch_bounds__(256, 2) mega(Params p) {
;   extern __shared__ __attribute__((aligned(16))) char smem[];
amdhsa.kernels:
  - .agpr_count:     0
    .args:
      - .offset:         0
        .size:           192
        .value_kind:     by_value
      - .offset:         192
        .size:           4
        .value_kind:     hidden_block_count_x
      - .offset:         196
        .size:           4
        .value_kind:     hidden_block_count_y
      - .offset:         200
        .size:           4
        .value_kind:     hidden_block_count_z
      - .offset:         204
        .size:           2
        .value_kind:     hidden_group_size_x
      - .offset:         206
        .size:           2
        .value_kind:     hidden_group_size_y
      - .offset:         208
        .size:           2
        .value_kind:     hidden_group_size_z
      - .offset:         210
        .size:           2
        .value_kind:     hidden_remainder_x
      - .offset:         212
        .size:           2
        .value_kind:     hidden_remainder_y
      - .offset:         214
        .size:           2
        .value_kind:     hidden_remainder_z
      - .offset:         232
        .size:           8
        .value_kind:     hidden_global_offset_x
      - .offset:         240
        .size:           8
        .value_kind:     hidden_global_offset_y
      - .offset:         248
        .size:           8
        .value_kind:     hidden_global_offset_z
      - .offset:         256
        .size:           2
        .value_kind:     hidden_grid_dims
      - .offset:         312
        .size:           4
        .value_kind:     hidden_dynamic_lds_size
    .group_segment_fixed_size: 0
    .kernarg_segment_align: 8
    .kernarg_segment_size: 448
    .language:       OpenCL C
    .language_version:
      - 2
      - 0
    .max_flat_workgroup_size: 256
    .name:           _Z4mega6Params
    .private_segment_fixed_size: 0
    .sgpr_count:     108
    .sgpr_spill_count: 0
    .symbol:         _Z4mega6Params.kd
    .uniform_work_group_size: 1
    .uses_dynamic_stack: false
    .vgpr_count:     246
    .vgpr_spill_count: 0
    .wavefront_size: 64
